# GEMM mainloop: loop-control and LDS-offset SALU moved from MFMA segment tails (between last MFMA and barrier) into the preceding load segments
# speedup vs baseline: 1.0094x; 1.0007x over previous
; #define PG8_STAGE(bufoff, gbase, voff) do { _Pragma("unroll") for (int _i = 0; _i < 2; ++_i) \
;         __builtin_amdgcn_global_load_lds((const unsigned*)((const char*)(gbase) + (voff)[_i]), (LAS unsigned*)(lds + (bufoff) + ldsw + _i * 8192), 16, 0, 0); } while (0)
; #define PG8_LDA(dst, b, h) do { _Pragma("unroll") for (int m = 0; m < 4; ++m) _Pragma("unroll") for (int k = 0; k < 2; ++k) dst[m][k] = *(const LAS bf16x8*)(lds + PG8_SA(b, h) + aoff + m * 2048 + k * 1024); } while (0)
; #define PG8_LDB(dst, b, h) do { _Pragma("unroll") for (int n = 0; n < 2; ++n) _Pragma("unroll") for (int k = 0; k < 2; ++k) dst[n][k] = *(const LAS bf16x8*)(lds + PG8_SB(b, h) + boff + n * 2048 + k * 1024); } while (0)
; #define PG8_MMA(ai, bj, At, Bt) do { __builtin_amdgcn_s_setprio(1); _Pragma("unroll") for (int m = 0; m < 4; ++m) _Pragma("unroll") for (int n = 0; n < 2; ++n) _Pragma("unroll") for (int k = 0; k < 2; ++k) \
;         acc[ai][bj][m][n] = __builtin_amdgcn_mfma_f32_16x16x32_bf16(Bt[n][k], At[m][k], acc[ai][bj][m][n], 0, 0, 0); __builtin_amdgcn_s_setprio(0); } while (0)
; #define PG8_WAIT_V(n) asm volatile("s_waitcnt vmcnt(" #n ")" ::: "memory")
; #define PG8_WAIT_L(n) asm volatile("s_waitcnt lgkmcnt(" #n ")" ::: "memory")
; #define PG8_BAR __builtin_amdgcn_s_barrier()
; #define PG8_SCHED __builtin_amdgcn_sched_barrier(0)
; template <class Epi>
; DI void gemm_phase(LAS unsigned char* lds, const Gemm g, const StaticOrder& S, const Epi& E, const int tid) {
;     ...
;             PG8_WAIT_V(6); PG8_BAR; PG8_MMA(1, 1, At, B1); PG8_BAR;
;             PG8_LDB(B0, 1, 0); PG8_SCHED; PG8_LDA(At, 1, 0); PG8_STAGE(PG8_SA(0, 1), a2 + hstep, voffA);
;             PG8_WAIT_L(8); PG8_BAR; PG8_WAIT_L(0); PG8_MMA(0, 0, At, B0); PG8_BAR; PG8_SCHED;
;             PG8_LDB(B1, 1, 1); PG8_STAGE(PG8_SB(1, 0), b3, voffB);
;             PG8_BAR; PG8_WAIT_L(0); PG8_MMA(0, 1, At, B1); PG8_BAR;
;             PG8_LDA(At, 1, 1); PG8_STAGE(PG8_SA(1, 0), a3, voffA);
;             PG8_BAR; PG8_WAIT_L(0); PG8_MMA(1, 0, At, B0); PG8_BAR; PG8_SCHED;
;             PG8_STAGE(PG8_SB(1, 1), b3 + hstep, voffB);
;             PG8_WAIT_V(6); PG8_BAR; PG8_MMA(1, 1, At, B1); PG8_BAR;
.LBB0_742:
	s_add_u32 s20, s20, 0x80
	s_addc_u32 s21, s21, 0
	s_add_u32 s81, s18, 0x100
	s_addc_u32 s82, s19, 0
	s_mov_b32 s18, 0
	ds_read_b128 v[138:141], v212
	ds_read_b128 v[150:153], v212 offset:1024
	ds_read_b128 v[154:157], v212 offset:2048
	ds_read_b128 v[158:161], v212 offset:3072
	s_add_i32 s83, s18, 2
	s_add_u32 s22, s20, 0x80
	s_addc_u32 s19, s21, 0
	s_cmp_eq_u32 s60, s18
	s_cselect_b32 s18, s8, s22
	s_cselect_b32 s19, s9, s19
	s_cselect_b32 s23, s17, s82
	s_cselect_b32 s22, s16, s81
	s_add_i32 m0, s49, 0xc000
	ds_read_b128 v[162:165], v148
	ds_read_b128 v[166:169], v148 offset:1024
	ds_read_b128 v[170:173], v148 offset:2048
	ds_read_b128 v[174:177], v148 offset:3072
	ds_read_b128 v[178:181], v148 offset:4096
	ds_read_b128 v[182:185], v148 offset:5120
	ds_read_b128 v[186:189], v148 offset:6144
	ds_read_b128 v[190:193], v148 offset:7168
	global_load_lds_dwordx4 v134, s[20:21]
	s_add_i32 m0, s49, 0xe000
	s_nop 0
	global_load_lds_dwordx4 v136, s[20:21]
	s_waitcnt lgkmcnt(8)
	s_barrier
	s_waitcnt lgkmcnt(0)
	s_setprio 1
	v_mfma_f32_16x16x32_bf16 v[24:27], v[138:141], v[162:165], 0
	v_mfma_f32_16x16x32_bf16 v[28:31], v[154:157], v[162:165], 0
	v_mfma_f32_16x16x32_bf16 v[16:19], v[138:141], v[170:173], 0
	v_mfma_f32_16x16x32_bf16 v[20:23], v[154:157], v[170:173], 0
	v_mfma_f32_16x16x32_bf16 v[8:11], v[138:141], v[178:181], 0
	v_mfma_f32_16x16x32_bf16 v[12:15], v[154:157], v[178:181], 0
	v_mfma_f32_16x16x32_bf16 v[0:3], v[138:141], v[186:189], 0
	v_mfma_f32_16x16x32_bf16 v[4:7], v[154:157], v[186:189], 0
	v_mfma_f32_16x16x32_bf16 v[24:27], v[150:153], v[166:169], v[24:27]
	v_mfma_f32_16x16x32_bf16 v[28:31], v[158:161], v[166:169], v[28:31]
	v_mfma_f32_16x16x32_bf16 v[16:19], v[150:153], v[174:177], v[16:19]
	v_mfma_f32_16x16x32_bf16 v[20:23], v[158:161], v[174:177], v[20:23]
	v_mfma_f32_16x16x32_bf16 v[8:11], v[150:153], v[182:185], v[8:11]
	v_mfma_f32_16x16x32_bf16 v[12:15], v[158:161], v[182:185], v[12:15]
	v_mfma_f32_16x16x32_bf16 v[0:3], v[150:153], v[190:193], v[0:3]
	v_mfma_f32_16x16x32_bf16 v[4:7], v[158:161], v[190:193], v[4:7]
	s_setprio 0
	s_barrier
	s_add_i32 s89, 0, 0x14000
	s_add_i32 vcc_lo, s26, s4
	s_mov_b32 m0, vcc_lo
	ds_read_b128 v[194:197], v213
	ds_read_b128 v[200:203], v213 offset:1024
	ds_read_b128 v[204:207], v213 offset:2048
	ds_read_b128 v[208:211], v213 offset:3072
	global_load_lds_dwordx4 v198, s[22:23]
	s_add_i32 m0, vcc_lo, 0x2000
	s_nop 0
	global_load_lds_dwordx4 v128, s[22:23]
	s_barrier
	s_waitcnt lgkmcnt(0)
	s_setprio 1
	v_mfma_f32_16x16x32_bf16 v[88:91], v[194:197], v[162:165], 0
	v_mfma_f32_16x16x32_bf16 v[96:99], v[204:207], v[162:165], 0
	v_mfma_f32_16x16x32_bf16 v[80:83], v[194:197], v[170:173], 0
	v_mfma_f32_16x16x32_bf16 v[84:87], v[204:207], v[170:173], 0
	v_mfma_f32_16x16x32_bf16 v[72:75], v[194:197], v[178:181], 0
	v_mfma_f32_16x16x32_bf16 v[76:79], v[204:207], v[178:181], 0
	v_mfma_f32_16x16x32_bf16 v[56:59], v[194:197], v[186:189], 0
	v_mfma_f32_16x16x32_bf16 v[64:67], v[204:207], v[186:189], 0
	v_mfma_f32_16x16x32_bf16 v[88:91], v[200:203], v[166:169], v[88:91]
	v_mfma_f32_16x16x32_bf16 v[96:99], v[208:211], v[166:169], v[96:99]
	v_mfma_f32_16x16x32_bf16 v[80:83], v[200:203], v[174:177], v[80:83]
	v_mfma_f32_16x16x32_bf16 v[84:87], v[208:211], v[174:177], v[84:87]
	v_mfma_f32_16x16x32_bf16 v[72:75], v[200:203], v[182:185], v[72:75]
	v_mfma_f32_16x16x32_bf16 v[76:79], v[208:211], v[182:185], v[76:79]
	v_mfma_f32_16x16x32_bf16 v[56:59], v[200:203], v[190:193], v[56:59]
	v_mfma_f32_16x16x32_bf16 v[64:67], v[208:211], v[190:193], v[64:67]
	s_setprio 0
	s_mov_b32 m0, s49
	s_barrier
	ds_read_b128 v[162:165], v148 offset:16384
	ds_read_b128 v[166:169], v148 offset:17408
	ds_read_b128 v[170:173], v148 offset:18432
	ds_read_b128 v[174:177], v148 offset:19456
	ds_read_b128 v[178:181], v148 offset:20480
	ds_read_b128 v[182:185], v148 offset:21504
	ds_read_b128 v[186:189], v148 offset:22528
	ds_read_b128 v[190:193], v148 offset:23552
	global_load_lds_dwordx4 v132, s[18:19]
	s_mov_b32 m0, s52
	s_nop 0
	global_load_lds_dwordx4 v130, s[18:19]
	s_barrier
	s_waitcnt lgkmcnt(0)
	s_setprio 1
	v_mfma_f32_16x16x32_bf16 v[60:63], v[138:141], v[162:165], 0
	v_mfma_f32_16x16x32_bf16 v[68:71], v[154:157], v[162:165], 0
	v_mfma_f32_16x16x32_bf16 v[48:51], v[138:141], v[170:173], 0
	v_mfma_f32_16x16x32_bf16 v[52:55], v[154:157], v[170:173], 0
	v_mfma_f32_16x16x32_bf16 v[40:43], v[138:141], v[178:181], 0
	v_mfma_f32_16x16x32_bf16 v[44:47], v[154:157], v[178:181], 0
	v_mfma_f32_16x16x32_bf16 v[32:35], v[138:141], v[186:189], 0
	v_mfma_f32_16x16x32_bf16 v[36:39], v[154:157], v[186:189], 0
	v_mfma_f32_16x16x32_bf16 v[60:63], v[150:153], v[166:169], v[60:63]
	v_mfma_f32_16x16x32_bf16 v[68:71], v[158:161], v[166:169], v[68:71]
	v_mfma_f32_16x16x32_bf16 v[48:51], v[150:153], v[174:177], v[48:51]
	v_mfma_f32_16x16x32_bf16 v[52:55], v[158:161], v[174:177], v[52:55]
	v_mfma_f32_16x16x32_bf16 v[40:43], v[150:153], v[182:185], v[40:43]
	v_mfma_f32_16x16x32_bf16 v[44:47], v[158:161], v[182:185], v[44:47]
	v_mfma_f32_16x16x32_bf16 v[32:35], v[150:153], v[190:193], v[32:35]
	v_mfma_f32_16x16x32_bf16 v[36:39], v[158:161], v[190:193], v[36:39]
	s_setprio 0
	s_barrier
	s_add_u32 s22, s22, s84
	s_addc_u32 s23, s23, 0
	s_add_i32 s89, s89, s4
	s_mov_b32 m0, s89
	s_nop 0
	global_load_lds_dwordx4 v198, s[22:23]
	s_add_i32 m0, s89, 0x2000
	s_nop 0
	global_load_lds_dwordx4 v128, s[22:23]
	s_add_i32 s22, 0, 0x18000
	s_waitcnt vmcnt(6)
	s_barrier
; #define PG8_STAGE(bufoff, gbase, voff) do { _Pragma("unroll") for (int _i = 0; _i < 2; ++_i) \
;         __builtin_amdgcn_global_load_lds((const unsigned*)((const char*)(gbase) + (voff)[_i]), (LAS unsigned*)(lds + (bufoff) + ldsw + _i * 8192), 16, 0, 0); } while (0)
; #define PG8_LDA(dst, b, h) do { _Pragma("unroll") for (int m = 0; m < 4; ++m) _Pragma("unroll") for (int k = 0; k < 2; ++k) dst[m][k] = *(const LAS bf16x8*)(lds + PG8_SA(b, h) + aoff + m * 2048 + k * 1024); } while (0)
; #define PG8_LDB(dst, b, h) do { _Pragma("unroll") for (int n = 0; n < 2; ++n) _Pragma("unroll") for (int k = 0; k < 2; ++k) dst[n][k] = *(const LAS bf16x8*)(lds + PG8_SB(b, h) + boff + n * 2048 + k * 1024); } while (0)
; #define PG8_MMA(ai, bj, At, Bt) do { __builtin_amdgcn_s_setprio(1); _Pragma("unroll") for (int m = 0; m < 4; ++m) _Pragma("unroll") for (int n = 0; n < 2; ++n) _Pragma("unroll") for (int k = 0; k < 2; ++k) \
;         acc[ai][bj][m][n] = __builtin_amdgcn_mfma_f32_16x16x32_bf16(Bt[n][k], At[m][k], acc[ai][bj][m][n], 0, 0, 0); __builtin_amdgcn_s_setprio(0); } while (0)
; #define PG8_WAIT_V(n) asm volatile("s_waitcnt vmcnt(" #n ")" ::: "memory")
; #define PG8_WAIT_L(n) asm volatile("s_waitcnt lgkmcnt(" #n ")" ::: "memory")
; #define PG8_BAR __builtin_amdgcn_s_barrier()
; #define PG8_SCHED __builtin_amdgcn_sched_barrier(0)
; template <class Epi>
; DI void gemm_phase(LAS unsigned char* lds, const Gemm g, const StaticOrder& S, const Epi& E, const int tid) {
;     ...
;             PG8_WAIT_V(6); PG8_BAR; PG8_MMA(1, 1, At, B1); PG8_BAR;
;             PG8_LDB(B0, 1, 0); PG8_SCHED; PG8_LDA(At, 1, 0); PG8_STAGE(PG8_SA(0, 1), a2 + hstep, voffA);
;             PG8_WAIT_L(8); PG8_BAR; PG8_WAIT_L(0); PG8_MMA(0, 0, At, B0); PG8_BAR; PG8_SCHED;
;             PG8_LDB(B1, 1, 1); PG8_STAGE(PG8_SB(1, 0), b3, voffB);
;             PG8_BAR; PG8_WAIT_L(0); PG8_MMA(0, 1, At, B1); PG8_BAR;
;             PG8_LDA(At, 1, 1); PG8_STAGE(PG8_SA(1, 0), a3, voffA);
;             PG8_BAR; PG8_WAIT_L(0); PG8_MMA(1, 0, At, B0); PG8_BAR; PG8_SCHED;
;             PG8_STAGE(PG8_SB(1, 1), b3 + hstep, voffB);
;             PG8_WAIT_V(6); PG8_BAR; PG8_MMA(1, 1, At, B1); PG8_BAR;
	s_setprio 1
	v_mfma_f32_16x16x32_bf16 v[120:123], v[194:197], v[162:165], 0
	v_mfma_f32_16x16x32_bf16 v[124:127], v[204:207], v[162:165], 0
	v_mfma_f32_16x16x32_bf16 v[112:115], v[194:197], v[170:173], 0
	v_mfma_f32_16x16x32_bf16 v[116:119], v[204:207], v[170:173], 0
	v_mfma_f32_16x16x32_bf16 v[104:107], v[194:197], v[178:181], 0
	v_mfma_f32_16x16x32_bf16 v[108:111], v[204:207], v[178:181], 0
	v_mfma_f32_16x16x32_bf16 v[92:95], v[194:197], v[186:189], 0
	v_mfma_f32_16x16x32_bf16 v[100:103], v[204:207], v[186:189], 0
	v_mfma_f32_16x16x32_bf16 v[120:123], v[200:203], v[166:169], v[120:123]
	v_mfma_f32_16x16x32_bf16 v[124:127], v[208:211], v[166:169], v[124:127]
	v_mfma_f32_16x16x32_bf16 v[112:115], v[200:203], v[174:177], v[112:115]
	v_mfma_f32_16x16x32_bf16 v[116:119], v[208:211], v[174:177], v[116:119]
	v_mfma_f32_16x16x32_bf16 v[104:107], v[200:203], v[182:185], v[104:107]
	v_mfma_f32_16x16x32_bf16 v[108:111], v[208:211], v[182:185], v[108:111]
	v_mfma_f32_16x16x32_bf16 v[92:95], v[200:203], v[190:193], v[92:95]
	v_mfma_f32_16x16x32_bf16 v[100:103], v[208:211], v[190:193], v[100:103]
	s_setprio 0
	s_barrier
	ds_read_b128 v[138:141], v214
	ds_read_b128 v[150:153], v214 offset:1024
	ds_read_b128 v[154:157], v214 offset:2048
	ds_read_b128 v[158:161], v214 offset:3072
	s_add_u32 s18, s18, s84
	s_addc_u32 s19, s19, 0
	s_mov_b32 m0, s53
	ds_read_b128 v[162:165], v148 offset:32768
	ds_read_b128 v[166:169], v148 offset:33792
	ds_read_b128 v[170:173], v148 offset:34816
	ds_read_b128 v[174:177], v148 offset:35840
	ds_read_b128 v[178:181], v148 offset:36864
	ds_read_b128 v[182:185], v148 offset:37888
	ds_read_b128 v[186:189], v148 offset:38912
	ds_read_b128 v[190:193], v148 offset:39936
	global_load_lds_dwordx4 v132, s[18:19]
	s_mov_b32 m0, s54
	s_nop 0
	global_load_lds_dwordx4 v130, s[18:19]
	s_waitcnt lgkmcnt(8)
	s_barrier
	s_waitcnt lgkmcnt(0)
	s_setprio 1
	v_mfma_f32_16x16x32_bf16 v[24:27], v[138:141], v[162:165], v[24:27]
	v_mfma_f32_16x16x32_bf16 v[28:31], v[154:157], v[162:165], v[28:31]
	v_mfma_f32_16x16x32_bf16 v[16:19], v[138:141], v[170:173], v[16:19]
	v_mfma_f32_16x16x32_bf16 v[20:23], v[154:157], v[170:173], v[20:23]
	v_mfma_f32_16x16x32_bf16 v[8:11], v[138:141], v[178:181], v[8:11]
	v_mfma_f32_16x16x32_bf16 v[12:15], v[154:157], v[178:181], v[12:15]
	v_mfma_f32_16x16x32_bf16 v[0:3], v[138:141], v[186:189], v[0:3]
	v_mfma_f32_16x16x32_bf16 v[4:7], v[154:157], v[186:189], v[4:7]
	v_mfma_f32_16x16x32_bf16 v[24:27], v[150:153], v[166:169], v[24:27]
	v_mfma_f32_16x16x32_bf16 v[28:31], v[158:161], v[166:169], v[28:31]
	v_mfma_f32_16x16x32_bf16 v[16:19], v[150:153], v[174:177], v[16:19]
	v_mfma_f32_16x16x32_bf16 v[20:23], v[158:161], v[174:177], v[20:23]
	v_mfma_f32_16x16x32_bf16 v[8:11], v[150:153], v[182:185], v[8:11]
	v_mfma_f32_16x16x32_bf16 v[12:15], v[158:161], v[182:185], v[12:15]
	v_mfma_f32_16x16x32_bf16 v[0:3], v[150:153], v[190:193], v[0:3]
	v_mfma_f32_16x16x32_bf16 v[4:7], v[158:161], v[190:193], v[4:7]
	s_setprio 0
	s_barrier
	s_add_i32 s18, 0, 0x1c000
	s_add_i32 s19, s22, s4
	s_mov_b32 m0, s19
	ds_read_b128 v[194:197], v215
	ds_read_b128 v[200:203], v215 offset:1024
	ds_read_b128 v[204:207], v215 offset:2048
	ds_read_b128 v[208:211], v215 offset:3072
	s_add_i32 vcc_hi, s60, 2
	s_cmp_eq_u32 vcc_hi, s83
	s_cselect_b32 s100, s16, s81
	s_cselect_b32 s101, s17, s82
	s_add_u32 s100, s100, 0x80
	s_addc_u32 s101, s101, 0
	global_load_lds_dwordx4 v198, s[100:101]
	s_add_i32 m0, s19, 0x2000
	s_nop 0
	global_load_lds_dwordx4 v128, s[100:101]
	s_barrier
	s_waitcnt lgkmcnt(0)
	s_setprio 1
	v_mfma_f32_16x16x32_bf16 v[88:91], v[194:197], v[162:165], v[88:91]
	v_mfma_f32_16x16x32_bf16 v[96:99], v[204:207], v[162:165], v[96:99]
	v_mfma_f32_16x16x32_bf16 v[80:83], v[194:197], v[170:173], v[80:83]
	v_mfma_f32_16x16x32_bf16 v[84:87], v[204:207], v[170:173], v[84:87]
	v_mfma_f32_16x16x32_bf16 v[72:75], v[194:197], v[178:181], v[72:75]
	v_mfma_f32_16x16x32_bf16 v[76:79], v[204:207], v[178:181], v[76:79]
	v_mfma_f32_16x16x32_bf16 v[56:59], v[194:197], v[186:189], v[56:59]
	v_mfma_f32_16x16x32_bf16 v[64:67], v[204:207], v[186:189], v[64:67]
	v_mfma_f32_16x16x32_bf16 v[88:91], v[200:203], v[166:169], v[88:91]
	v_mfma_f32_16x16x32_bf16 v[96:99], v[208:211], v[166:169], v[96:99]
	v_mfma_f32_16x16x32_bf16 v[80:83], v[200:203], v[174:177], v[80:83]
	v_mfma_f32_16x16x32_bf16 v[84:87], v[208:211], v[174:177], v[84:87]
	v_mfma_f32_16x16x32_bf16 v[72:75], v[200:203], v[182:185], v[72:75]
	v_mfma_f32_16x16x32_bf16 v[76:79], v[208:211], v[182:185], v[76:79]
	v_mfma_f32_16x16x32_bf16 v[56:59], v[200:203], v[190:193], v[56:59]
	v_mfma_f32_16x16x32_bf16 v[64:67], v[208:211], v[190:193], v[64:67]
	s_setprio 0
	s_mov_b32 m0, s55
	s_barrier
	ds_read_b128 v[162:165], v148 offset:49152
	ds_read_b128 v[166:169], v148 offset:50176
	ds_read_b128 v[170:173], v148 offset:51200
	ds_read_b128 v[174:177], v148 offset:52224
	ds_read_b128 v[178:181], v148 offset:53248
	ds_read_b128 v[182:185], v148 offset:54272
	ds_read_b128 v[186:189], v148 offset:55296
	ds_read_b128 v[190:193], v148 offset:56320
	s_add_u32 s100, s20, 0x80
	s_addc_u32 s101, s21, 0
	s_add_i32 vcc_hi, s60, 2
	s_cmp_eq_u32 vcc_hi, s83
	s_cselect_b32 s100, s8, s100
	s_cselect_b32 s101, s9, s101
	s_add_u32 s100, s100, 0x80
	s_addc_u32 s101, s101, 0
	global_load_lds_dwordx4 v132, s[100:101]
	s_mov_b32 m0, s56
	s_nop 0
	global_load_lds_dwordx4 v130, s[100:101]
	s_barrier
; #define PG8_STAGE(bufoff, gbase, voff) do { _Pragma("unroll") for (int _i = 0; _i < 2; ++_i) \
;         __builtin_amdgcn_global_load_lds((const unsigned*)((const char*)(gbase) + (voff)[_i]), (LAS unsigned*)(lds + (bufoff) + ldsw + _i * 8192), 16, 0, 0); } while (0)
; #define PG8_LDA(dst, b, h) do { _Pragma("unroll") for (int m = 0; m < 4; ++m) _Pragma("unroll") for (int k = 0; k < 2; ++k) dst[m][k] = *(const LAS bf16x8*)(lds + PG8_SA(b, h) + aoff + m * 2048 + k * 1024); } while (0)
; #define PG8_LDB(dst, b, h) do { _Pragma("unroll") for (int n = 0; n < 2; ++n) _Pragma("unroll") for (int k = 0; k < 2; ++k) dst[n][k] = *(const LAS bf16x8*)(lds + PG8_SB(b, h) + boff + n * 2048 + k * 1024); } while (0)
; #define PG8_MMA(ai, bj, At, Bt) do { __builtin_amdgcn_s_setprio(1); _Pragma("unroll") for (int m = 0; m < 4; ++m) _Pragma("unroll") for (int n = 0; n < 2; ++n) _Pragma("unroll") for (int k = 0; k < 2; ++k) \
;         acc[ai][bj][m][n] = __builtin_amdgcn_mfma_f32_16x16x32_bf16(Bt[n][k], At[m][k], acc[ai][bj][m][n], 0, 0, 0); __builtin_amdgcn_s_setprio(0); } while (0)
; #define PG8_WAIT_V(n) asm volatile("s_waitcnt vmcnt(" #n ")" ::: "memory")
; #define PG8_WAIT_L(n) asm volatile("s_waitcnt lgkmcnt(" #n ")" ::: "memory")
; #define PG8_BAR __builtin_amdgcn_s_barrier()
; #define PG8_SCHED __builtin_amdgcn_sched_barrier(0)
; template <class Epi>
; DI void gemm_phase(LAS unsigned char* lds, const Gemm g, const StaticOrder& S, const Epi& E, const int tid) {
;     ...
;         for (int t = 0; t < nt; t += 2) {
;             const bool last = (t == nt - 2);
;             const char* a1 = cA + (size_t)(t + 1) * kstep;
;             const char* a2 = last ? nA : cA + (size_t)(t + 2) * kstep; const char* b2 = last ? nB : cB + (size_t)(t + 2) * kstep;
;             const char* a3 = a2 + kstep; const char* b3 = b2 + kstep;
;             PG8_LDB(B0, 0, 0); PG8_SCHED; PG8_LDA(At, 0, 0); PG8_STAGE(PG8_SA(1, 1), a1 + hstep, voffA);
;             PG8_WAIT_L(8); PG8_BAR; PG8_WAIT_L(0); PG8_MMA(0, 0, At, B0); PG8_BAR; PG8_SCHED;
;             PG8_LDB(B1, 0, 1); PG8_STAGE(PG8_SB(0, 0), b2, voffB);
;             PG8_BAR; PG8_WAIT_L(0); PG8_MMA(0, 1, At, B1); PG8_BAR;
;     ...
;             PG8_STAGE(PG8_SB(1, 1), b3 + hstep, voffB);
;             PG8_WAIT_V(6); PG8_BAR; PG8_MMA(1, 1, At, B1); PG8_BAR;
	s_waitcnt lgkmcnt(0)
	s_setprio 1
	v_mfma_f32_16x16x32_bf16 v[60:63], v[138:141], v[162:165], v[60:63]
	v_mfma_f32_16x16x32_bf16 v[68:71], v[154:157], v[162:165], v[68:71]
	v_mfma_f32_16x16x32_bf16 v[48:51], v[138:141], v[170:173], v[48:51]
	v_mfma_f32_16x16x32_bf16 v[52:55], v[154:157], v[170:173], v[52:55]
	v_mfma_f32_16x16x32_bf16 v[40:43], v[138:141], v[178:181], v[40:43]
	v_mfma_f32_16x16x32_bf16 v[44:47], v[154:157], v[178:181], v[44:47]
	v_mfma_f32_16x16x32_bf16 v[32:35], v[138:141], v[186:189], v[32:35]
	v_mfma_f32_16x16x32_bf16 v[36:39], v[154:157], v[186:189], v[36:39]
	v_mfma_f32_16x16x32_bf16 v[60:63], v[150:153], v[166:169], v[60:63]
	v_mfma_f32_16x16x32_bf16 v[68:71], v[158:161], v[166:169], v[68:71]
	v_mfma_f32_16x16x32_bf16 v[48:51], v[150:153], v[174:177], v[48:51]
	v_mfma_f32_16x16x32_bf16 v[52:55], v[158:161], v[174:177], v[52:55]
	v_mfma_f32_16x16x32_bf16 v[40:43], v[150:153], v[182:185], v[40:43]
	v_mfma_f32_16x16x32_bf16 v[44:47], v[158:161], v[182:185], v[44:47]
	v_mfma_f32_16x16x32_bf16 v[32:35], v[150:153], v[190:193], v[32:35]
	v_mfma_f32_16x16x32_bf16 v[36:39], v[158:161], v[190:193], v[36:39]
	s_setprio 0
	s_barrier
	s_add_i32 s18, s18, s4
	s_add_i32 vcc_hi, s60, 2
	s_cmp_eq_u32 vcc_hi, s83
	s_cselect_b32 s100, s16, s81
	s_cselect_b32 s101, s17, s82
	s_add_u32 s100, s100, s84
	s_addc_u32 s101, s101, 0
	s_add_u32 s100, s100, 0x80
	s_addc_u32 s101, s101, 0
	s_mov_b32 m0, s18
	s_nop 0
	global_load_lds_dwordx4 v198, s[100:101]
	s_add_i32 m0, s18, 0x2000
	s_nop 0
	global_load_lds_dwordx4 v128, s[100:101]
	s_add_u32 s20, s20, 0x100
	s_addc_u32 s21, s21, 0
	s_add_u32 s81, s81, 0x100
	s_addc_u32 s82, s82, 0
	s_mov_b32 s18, s83
	s_cmp_ge_u32 s83, s57
	s_waitcnt vmcnt(6)
	s_barrier
	s_setprio 1
	v_mfma_f32_16x16x32_bf16 v[120:123], v[194:197], v[162:165], v[120:123]
	v_mfma_f32_16x16x32_bf16 v[124:127], v[204:207], v[162:165], v[124:127]
	v_mfma_f32_16x16x32_bf16 v[112:115], v[194:197], v[170:173], v[112:115]
	v_mfma_f32_16x16x32_bf16 v[116:119], v[204:207], v[170:173], v[116:119]
	v_mfma_f32_16x16x32_bf16 v[104:107], v[194:197], v[178:181], v[104:107]
	v_mfma_f32_16x16x32_bf16 v[108:111], v[204:207], v[178:181], v[108:111]
	v_mfma_f32_16x16x32_bf16 v[92:95], v[194:197], v[186:189], v[92:95]
	v_mfma_f32_16x16x32_bf16 v[100:103], v[204:207], v[186:189], v[100:103]
	v_mfma_f32_16x16x32_bf16 v[120:123], v[200:203], v[166:169], v[120:123]
	v_mfma_f32_16x16x32_bf16 v[124:127], v[208:211], v[166:169], v[124:127]
	v_mfma_f32_16x16x32_bf16 v[112:115], v[200:203], v[174:177], v[112:115]
	v_mfma_f32_16x16x32_bf16 v[116:119], v[208:211], v[174:177], v[116:119]
	v_mfma_f32_16x16x32_bf16 v[104:107], v[200:203], v[182:185], v[104:107]
	v_mfma_f32_16x16x32_bf16 v[108:111], v[208:211], v[182:185], v[108:111]
	v_mfma_f32_16x16x32_bf16 v[92:95], v[200:203], v[190:193], v[92:95]
	v_mfma_f32_16x16x32_bf16 v[100:103], v[208:211], v[190:193], v[100:103]
	s_setprio 0
	s_barrier
	s_cbranch_scc0 .LBB0_743
	s_branch .Lgemm_epi
.LBB0_743:
	ds_read_b128 v[138:141], v212
	ds_read_b128 v[150:153], v212 offset:1024
	ds_read_b128 v[154:157], v212 offset:2048
	ds_read_b128 v[158:161], v212 offset:3072
	s_add_i32 s83, s18, 2
	s_add_u32 s22, s20, 0x80
	s_addc_u32 s19, s21, 0
	s_cmp_eq_u32 s60, s18
	s_cselect_b32 s18, s8, s22
	s_cselect_b32 s19, s9, s19
	s_cselect_b32 s23, s17, s82
	s_cselect_b32 s22, s16, s81
	s_add_i32 m0, s49, 0xc000
	ds_read_b128 v[162:165], v148
	ds_read_b128 v[166:169], v148 offset:1024
	ds_read_b128 v[170:173], v148 offset:2048
	ds_read_b128 v[174:177], v148 offset:3072
	ds_read_b128 v[178:181], v148 offset:4096
	ds_read_b128 v[182:185], v148 offset:5120
	ds_read_b128 v[186:189], v148 offset:6144
	ds_read_b128 v[190:193], v148 offset:7168
	global_load_lds_dwordx4 v134, s[20:21]
	s_add_i32 m0, s49, 0xe000
	s_nop 0
	global_load_lds_dwordx4 v136, s[20:21]
	s_waitcnt lgkmcnt(8)
	s_barrier
	s_waitcnt lgkmcnt(0)
	s_setprio 1
	v_mfma_f32_16x16x32_bf16 v[24:27], v[138:141], v[162:165], v[24:27]
	v_mfma_f32_16x16x32_bf16 v[28:31], v[154:157], v[162:165], v[28:31]
	v_mfma_f32_16x16x32_bf16 v[16:19], v[138:141], v[170:173], v[16:19]
	v_mfma_f32_16x16x32_bf16 v[20:23], v[154:157], v[170:173], v[20:23]
	v_mfma_f32_16x16x32_bf16 v[8:11], v[138:141], v[178:181], v[8:11]
	v_mfma_f32_16x16x32_bf16 v[12:15], v[154:157], v[178:181], v[12:15]
	v_mfma_f32_16x16x32_bf16 v[0:3], v[138:141], v[186:189], v[0:3]
	v_mfma_f32_16x16x32_bf16 v[4:7], v[154:157], v[186:189], v[4:7]
	v_mfma_f32_16x16x32_bf16 v[24:27], v[150:153], v[166:169], v[24:27]
	v_mfma_f32_16x16x32_bf16 v[28:31], v[158:161], v[166:169], v[28:31]
	v_mfma_f32_16x16x32_bf16 v[16:19], v[150:153], v[174:177], v[16:19]
	v_mfma_f32_16x16x32_bf16 v[20:23], v[158:161], v[174:177], v[20:23]
	v_mfma_f32_16x16x32_bf16 v[8:11], v[150:153], v[182:185], v[8:11]
	v_mfma_f32_16x16x32_bf16 v[12:15], v[158:161], v[182:185], v[12:15]
	v_mfma_f32_16x16x32_bf16 v[0:3], v[150:153], v[190:193], v[0:3]
	v_mfma_f32_16x16x32_bf16 v[4:7], v[158:161], v[190:193], v[4:7]
	s_setprio 0
	s_barrier
	s_add_i32 s89, 0, 0x14000
	s_add_i32 vcc_lo, s26, s4
	s_mov_b32 m0, vcc_lo
	ds_read_b128 v[194:197], v213
	ds_read_b128 v[200:203], v213 offset:1024
	ds_read_b128 v[204:207], v213 offset:2048
	ds_read_b128 v[208:211], v213 offset:3072
	global_load_lds_dwordx4 v198, s[22:23]
	s_add_i32 m0, vcc_lo, 0x2000
	s_nop 0
	global_load_lds_dwordx4 v128, s[22:23]
	s_barrier
; #define PG8_STAGE(bufoff, gbase, voff) do { _Pragma("unroll") for (int _i = 0; _i < 2; ++_i) \
;         __builtin_amdgcn_global_load_lds((const unsigned*)((const char*)(gbase) + (voff)[_i]), (LAS unsigned*)(lds + (bufoff) + ldsw + _i * 8192), 16, 0, 0); } while (0)
; #define PG8_LDA(dst, b, h) do { _Pragma("unroll") for (int m = 0; m < 4; ++m) _Pragma("unroll") for (int k = 0; k < 2; ++k) dst[m][k] = *(const LAS bf16x8*)(lds + PG8_SA(b, h) + aoff + m * 2048 + k * 1024); } while (0)
; #define PG8_LDB(dst, b, h) do { _Pragma("unroll") for (int n = 0; n < 2; ++n) _Pragma("unroll") for (int k = 0; k < 2; ++k) dst[n][k] = *(const LAS bf16x8*)(lds + PG8_SB(b, h) + boff + n * 2048 + k * 1024); } while (0)
; #define PG8_MMA(ai, bj, At, Bt) do { __builtin_amdgcn_s_setprio(1); _Pragma("unroll") for (int m = 0; m < 4; ++m) _Pragma("unroll") for (int n = 0; n < 2; ++n) _Pragma("unroll") for (int k = 0; k < 2; ++k) \
;         acc[ai][bj][m][n] = __builtin_amdgcn_mfma_f32_16x16x32_bf16(Bt[n][k], At[m][k], acc[ai][bj][m][n], 0, 0, 0); __builtin_amdgcn_s_setprio(0); } while (0)
; #define PG8_WAIT_V(n) asm volatile("s_waitcnt vmcnt(" #n ")" ::: "memory")
; #define PG8_WAIT_L(n) asm volatile("s_waitcnt lgkmcnt(" #n ")" ::: "memory")
; #define PG8_BAR __builtin_amdgcn_s_barrier()
; #define PG8_SCHED __builtin_amdgcn_sched_barrier(0)
; template <class Epi>
; DI void gemm_phase(LAS unsigned char* lds, const Gemm g, const StaticOrder& S, const Epi& E, const int tid) {
;     ...
;             PG8_BAR; PG8_WAIT_L(0); PG8_MMA(0, 1, At, B1); PG8_BAR;
;             PG8_LDA(At, 0, 1); PG8_STAGE(PG8_SA(0, 0), a2, voffA);
;             PG8_BAR; PG8_WAIT_L(0); PG8_MMA(1, 0, At, B0); PG8_BAR; PG8_SCHED;
;             PG8_STAGE(PG8_SB(0, 1), b2 + hstep, voffB);
;             PG8_WAIT_V(6); PG8_BAR; PG8_MMA(1, 1, At, B1); PG8_BAR;
;             PG8_LDB(B0, 1, 0); PG8_SCHED; PG8_LDA(At, 1, 0); PG8_STAGE(PG8_SA(0, 1), a2 + hstep, voffA);
;             PG8_WAIT_L(8); PG8_BAR; PG8_WAIT_L(0); PG8_MMA(0, 0, At, B0); PG8_BAR; PG8_SCHED;
;             PG8_LDB(B1, 1, 1); PG8_STAGE(PG8_SB(1, 0), b3, voffB);
;             PG8_BAR; PG8_WAIT_L(0); PG8_MMA(0, 1, At, B1); PG8_BAR;
	s_waitcnt lgkmcnt(0)
	s_setprio 1
	v_mfma_f32_16x16x32_bf16 v[88:91], v[194:197], v[162:165], v[88:91]
	v_mfma_f32_16x16x32_bf16 v[96:99], v[204:207], v[162:165], v[96:99]
	v_mfma_f32_16x16x32_bf16 v[80:83], v[194:197], v[170:173], v[80:83]
	v_mfma_f32_16x16x32_bf16 v[84:87], v[204:207], v[170:173], v[84:87]
	v_mfma_f32_16x16x32_bf16 v[72:75], v[194:197], v[178:181], v[72:75]
	v_mfma_f32_16x16x32_bf16 v[76:79], v[204:207], v[178:181], v[76:79]
	v_mfma_f32_16x16x32_bf16 v[56:59], v[194:197], v[186:189], v[56:59]
	v_mfma_f32_16x16x32_bf16 v[64:67], v[204:207], v[186:189], v[64:67]
	v_mfma_f32_16x16x32_bf16 v[88:91], v[200:203], v[166:169], v[88:91]
	v_mfma_f32_16x16x32_bf16 v[96:99], v[208:211], v[166:169], v[96:99]
	v_mfma_f32_16x16x32_bf16 v[80:83], v[200:203], v[174:177], v[80:83]
	v_mfma_f32_16x16x32_bf16 v[84:87], v[208:211], v[174:177], v[84:87]
	v_mfma_f32_16x16x32_bf16 v[72:75], v[200:203], v[182:185], v[72:75]
	v_mfma_f32_16x16x32_bf16 v[76:79], v[208:211], v[182:185], v[76:79]
	v_mfma_f32_16x16x32_bf16 v[56:59], v[200:203], v[190:193], v[56:59]
	v_mfma_f32_16x16x32_bf16 v[64:67], v[208:211], v[190:193], v[64:67]
	s_setprio 0
	s_mov_b32 m0, s49
	s_barrier
	ds_read_b128 v[162:165], v148 offset:16384
	ds_read_b128 v[166:169], v148 offset:17408
	ds_read_b128 v[170:173], v148 offset:18432
	ds_read_b128 v[174:177], v148 offset:19456
	ds_read_b128 v[178:181], v148 offset:20480
	ds_read_b128 v[182:185], v148 offset:21504
	ds_read_b128 v[186:189], v148 offset:22528
	ds_read_b128 v[190:193], v148 offset:23552
	global_load_lds_dwordx4 v132, s[18:19]
	s_mov_b32 m0, s52
	s_nop 0
	global_load_lds_dwordx4 v130, s[18:19]
	s_barrier
	s_waitcnt lgkmcnt(0)
	s_setprio 1
	v_mfma_f32_16x16x32_bf16 v[60:63], v[138:141], v[162:165], v[60:63]
	v_mfma_f32_16x16x32_bf16 v[68:71], v[154:157], v[162:165], v[68:71]
	v_mfma_f32_16x16x32_bf16 v[48:51], v[138:141], v[170:173], v[48:51]
	v_mfma_f32_16x16x32_bf16 v[52:55], v[154:157], v[170:173], v[52:55]
	v_mfma_f32_16x16x32_bf16 v[40:43], v[138:141], v[178:181], v[40:43]
	v_mfma_f32_16x16x32_bf16 v[44:47], v[154:157], v[178:181], v[44:47]
	v_mfma_f32_16x16x32_bf16 v[32:35], v[138:141], v[186:189], v[32:35]
	v_mfma_f32_16x16x32_bf16 v[36:39], v[154:157], v[186:189], v[36:39]
	v_mfma_f32_16x16x32_bf16 v[60:63], v[150:153], v[166:169], v[60:63]
	v_mfma_f32_16x16x32_bf16 v[68:71], v[158:161], v[166:169], v[68:71]
	v_mfma_f32_16x16x32_bf16 v[48:51], v[150:153], v[174:177], v[48:51]
	v_mfma_f32_16x16x32_bf16 v[52:55], v[158:161], v[174:177], v[52:55]
	v_mfma_f32_16x16x32_bf16 v[40:43], v[150:153], v[182:185], v[40:43]
	v_mfma_f32_16x16x32_bf16 v[44:47], v[158:161], v[182:185], v[44:47]
	v_mfma_f32_16x16x32_bf16 v[32:35], v[150:153], v[190:193], v[32:35]
	v_mfma_f32_16x16x32_bf16 v[36:39], v[158:161], v[190:193], v[36:39]
	s_setprio 0
	s_barrier
	s_add_u32 s22, s22, s84
	s_addc_u32 s23, s23, 0
	s_add_i32 s89, s89, s4
	s_mov_b32 m0, s89
	s_nop 0
	global_load_lds_dwordx4 v198, s[22:23]
	s_add_i32 m0, s89, 0x2000
	s_nop 0
	global_load_lds_dwordx4 v128, s[22:23]
	s_add_i32 s22, 0, 0x18000
	s_waitcnt vmcnt(6)
	s_barrier
	s_setprio 1
	v_mfma_f32_16x16x32_bf16 v[120:123], v[194:197], v[162:165], v[120:123]
	v_mfma_f32_16x16x32_bf16 v[124:127], v[204:207], v[162:165], v[124:127]
	v_mfma_f32_16x16x32_bf16 v[112:115], v[194:197], v[170:173], v[112:115]
	v_mfma_f32_16x16x32_bf16 v[116:119], v[204:207], v[170:173], v[116:119]
	v_mfma_f32_16x16x32_bf16 v[104:107], v[194:197], v[178:181], v[104:107]
	v_mfma_f32_16x16x32_bf16 v[108:111], v[204:207], v[178:181], v[108:111]
	v_mfma_f32_16x16x32_bf16 v[92:95], v[194:197], v[186:189], v[92:95]
	v_mfma_f32_16x16x32_bf16 v[100:103], v[204:207], v[186:189], v[100:103]
	v_mfma_f32_16x16x32_bf16 v[120:123], v[200:203], v[166:169], v[120:123]
	v_mfma_f32_16x16x32_bf16 v[124:127], v[208:211], v[166:169], v[124:127]
	v_mfma_f32_16x16x32_bf16 v[112:115], v[200:203], v[174:177], v[112:115]
	v_mfma_f32_16x16x32_bf16 v[116:119], v[208:211], v[174:177], v[116:119]
	v_mfma_f32_16x16x32_bf16 v[104:107], v[200:203], v[182:185], v[104:107]
	v_mfma_f32_16x16x32_bf16 v[108:111], v[208:211], v[182:185], v[108:111]
	v_mfma_f32_16x16x32_bf16 v[92:95], v[200:203], v[190:193], v[92:95]
	v_mfma_f32_16x16x32_bf16 v[100:103], v[208:211], v[190:193], v[100:103]
	s_setprio 0
	s_barrier
	ds_read_b128 v[138:141], v214
	ds_read_b128 v[150:153], v214 offset:1024
	ds_read_b128 v[154:157], v214 offset:2048
	ds_read_b128 v[158:161], v214 offset:3072
	s_add_u32 s18, s18, s84
	s_addc_u32 s19, s19, 0
	s_mov_b32 m0, s53
	ds_read_b128 v[162:165], v148 offset:32768
	ds_read_b128 v[166:169], v148 offset:33792
	ds_read_b128 v[170:173], v148 offset:34816
	ds_read_b128 v[174:177], v148 offset:35840
	ds_read_b128 v[178:181], v148 offset:36864
	ds_read_b128 v[182:185], v148 offset:37888
	ds_read_b128 v[186:189], v148 offset:38912
	ds_read_b128 v[190:193], v148 offset:39936
	global_load_lds_dwordx4 v132, s[18:19]
	s_mov_b32 m0, s54
	s_nop 0
	global_load_lds_dwordx4 v130, s[18:19]
	s_waitcnt lgkmcnt(8)
	s_barrier
	s_waitcnt lgkmcnt(0)
	s_setprio 1
	v_mfma_f32_16x16x32_bf16 v[24:27], v[138:141], v[162:165], v[24:27]
	v_mfma_f32_16x16x32_bf16 v[28:31], v[154:157], v[162:165], v[28:31]
	v_mfma_f32_16x16x32_bf16 v[16:19], v[138:141], v[170:173], v[16:19]
	v_mfma_f32_16x16x32_bf16 v[20:23], v[154:157], v[170:173], v[20:23]
	v_mfma_f32_16x16x32_bf16 v[8:11], v[138:141], v[178:181], v[8:11]
	v_mfma_f32_16x16x32_bf16 v[12:15], v[154:157], v[178:181], v[12:15]
	v_mfma_f32_16x16x32_bf16 v[0:3], v[138:141], v[186:189], v[0:3]
	v_mfma_f32_16x16x32_bf16 v[4:7], v[154:157], v[186:189], v[4:7]
	v_mfma_f32_16x16x32_bf16 v[24:27], v[150:153], v[166:169], v[24:27]
	v_mfma_f32_16x16x32_bf16 v[28:31], v[158:161], v[166:169], v[28:31]
	v_mfma_f32_16x16x32_bf16 v[16:19], v[150:153], v[174:177], v[16:19]
	v_mfma_f32_16x16x32_bf16 v[20:23], v[158:161], v[174:177], v[20:23]
	v_mfma_f32_16x16x32_bf16 v[8:11], v[150:153], v[182:185], v[8:11]
	v_mfma_f32_16x16x32_bf16 v[12:15], v[158:161], v[182:185], v[12:15]
	v_mfma_f32_16x16x32_bf16 v[0:3], v[150:153], v[190:193], v[0:3]
	v_mfma_f32_16x16x32_bf16 v[4:7], v[158:161], v[190:193], v[4:7]
	s_setprio 0
	s_barrier
; #define PG8_STAGE(bufoff, gbase, voff) do { _Pragma("unroll") for (int _i = 0; _i < 2; ++_i) \
;         __builtin_amdgcn_global_load_lds((const unsigned*)((const char*)(gbase) + (voff)[_i]), (LAS unsigned*)(lds + (bufoff) + ldsw + _i * 8192), 16, 0, 0); } while (0)
; #define PG8_LDA(dst, b, h) do { _Pragma("unroll") for (int m = 0; m < 4; ++m) _Pragma("unroll") for (int k = 0; k < 2; ++k) dst[m][k] = *(const LAS bf16x8*)(lds + PG8_SA(b, h) + aoff + m * 2048 + k * 1024); } while (0)
; #define PG8_LDB(dst, b, h) do { _Pragma("unroll") for (int n = 0; n < 2; ++n) _Pragma("unroll") for (int k = 0; k < 2; ++k) dst[n][k] = *(const LAS bf16x8*)(lds + PG8_SB(b, h) + boff + n * 2048 + k * 1024); } while (0)
; #define PG8_MMA(ai, bj, At, Bt) do { __builtin_amdgcn_s_setprio(1); _Pragma("unroll") for (int m = 0; m < 4; ++m) _Pragma("unroll") for (int n = 0; n < 2; ++n) _Pragma("unroll") for (int k = 0; k < 2; ++k) \
;         acc[ai][bj][m][n] = __builtin_amdgcn_mfma_f32_16x16x32_bf16(Bt[n][k], At[m][k], acc[ai][bj][m][n], 0, 0, 0); __builtin_amdgcn_s_setprio(0); } while (0)
; #define PG8_WAIT_V(n) asm volatile("s_waitcnt vmcnt(" #n ")" ::: "memory")
; #define PG8_WAIT_L(n) asm volatile("s_waitcnt lgkmcnt(" #n ")" ::: "memory")
; #define PG8_BAR __builtin_amdgcn_s_barrier()
; #define PG8_SCHED __builtin_amdgcn_sched_barrier(0)
; template <class Epi>
; DI void gemm_phase(LAS unsigned char* lds, const Gemm g, const StaticOrder& S, const Epi& E, const int tid) {
;     ...
;             PG8_LDB(B1, 1, 1); PG8_STAGE(PG8_SB(1, 0), b3, voffB);
;             PG8_BAR; PG8_WAIT_L(0); PG8_MMA(0, 1, At, B1); PG8_BAR;
;             PG8_LDA(At, 1, 1); PG8_STAGE(PG8_SA(1, 0), a3, voffA);
;             PG8_BAR; PG8_WAIT_L(0); PG8_MMA(1, 0, At, B0); PG8_BAR; PG8_SCHED;
;             PG8_STAGE(PG8_SB(1, 1), b3 + hstep, voffB);
;             PG8_WAIT_V(6); PG8_BAR; PG8_MMA(1, 1, At, B1); PG8_BAR;
	s_add_i32 s18, 0, 0x1c000
	s_add_i32 s19, s22, s4
	s_mov_b32 m0, s19
	ds_read_b128 v[194:197], v215
	ds_read_b128 v[200:203], v215 offset:1024
	ds_read_b128 v[204:207], v215 offset:2048
	ds_read_b128 v[208:211], v215 offset:3072
	s_add_i32 vcc_hi, s60, 2
	s_cmp_eq_u32 vcc_hi, s83
	s_cselect_b32 s100, s16, s81
	s_cselect_b32 s101, s17, s82
	s_add_u32 s100, s100, 0x80
	s_addc_u32 s101, s101, 0
	global_load_lds_dwordx4 v198, s[100:101]
	s_add_i32 m0, s19, 0x2000
	s_nop 0
	global_load_lds_dwordx4 v128, s[100:101]
	s_barrier
	s_waitcnt lgkmcnt(0)
	s_setprio 1
	v_mfma_f32_16x16x32_bf16 v[88:91], v[194:197], v[162:165], v[88:91]
	v_mfma_f32_16x16x32_bf16 v[96:99], v[204:207], v[162:165], v[96:99]
	v_mfma_f32_16x16x32_bf16 v[80:83], v[194:197], v[170:173], v[80:83]
	v_mfma_f32_16x16x32_bf16 v[84:87], v[204:207], v[170:173], v[84:87]
	v_mfma_f32_16x16x32_bf16 v[72:75], v[194:197], v[178:181], v[72:75]
	v_mfma_f32_16x16x32_bf16 v[76:79], v[204:207], v[178:181], v[76:79]
	v_mfma_f32_16x16x32_bf16 v[56:59], v[194:197], v[186:189], v[56:59]
	v_mfma_f32_16x16x32_bf16 v[64:67], v[204:207], v[186:189], v[64:67]
	v_mfma_f32_16x16x32_bf16 v[88:91], v[200:203], v[166:169], v[88:91]
	v_mfma_f32_16x16x32_bf16 v[96:99], v[208:211], v[166:169], v[96:99]
	v_mfma_f32_16x16x32_bf16 v[80:83], v[200:203], v[174:177], v[80:83]
	v_mfma_f32_16x16x32_bf16 v[84:87], v[208:211], v[174:177], v[84:87]
	v_mfma_f32_16x16x32_bf16 v[72:75], v[200:203], v[182:185], v[72:75]
	v_mfma_f32_16x16x32_bf16 v[76:79], v[208:211], v[182:185], v[76:79]
	v_mfma_f32_16x16x32_bf16 v[56:59], v[200:203], v[190:193], v[56:59]
	v_mfma_f32_16x16x32_bf16 v[64:67], v[208:211], v[190:193], v[64:67]
	s_setprio 0
	s_mov_b32 m0, s55
	s_barrier
	ds_read_b128 v[162:165], v148 offset:49152
	ds_read_b128 v[166:169], v148 offset:50176
	ds_read_b128 v[170:173], v148 offset:51200
	ds_read_b128 v[174:177], v148 offset:52224
	ds_read_b128 v[178:181], v148 offset:53248
	ds_read_b128 v[182:185], v148 offset:54272
	ds_read_b128 v[186:189], v148 offset:55296
	ds_read_b128 v[190:193], v148 offset:56320
	s_add_u32 s100, s20, 0x80
	s_addc_u32 s101, s21, 0
	s_add_i32 vcc_hi, s60, 2
	s_cmp_eq_u32 vcc_hi, s83
	s_cselect_b32 s100, s8, s100
	s_cselect_b32 s101, s9, s101
	s_add_u32 s100, s100, 0x80
	s_addc_u32 s101, s101, 0
	global_load_lds_dwordx4 v132, s[100:101]
	s_mov_b32 m0, s56
	s_nop 0
	global_load_lds_dwordx4 v130, s[100:101]
	s_barrier
	s_waitcnt lgkmcnt(0)
	s_setprio 1
	v_mfma_f32_16x16x32_bf16 v[60:63], v[138:141], v[162:165], v[60:63]
	v_mfma_f32_16x16x32_bf16 v[68:71], v[154:157], v[162:165], v[68:71]
	v_mfma_f32_16x16x32_bf16 v[48:51], v[138:141], v[170:173], v[48:51]
	v_mfma_f32_16x16x32_bf16 v[52:55], v[154:157], v[170:173], v[52:55]
	v_mfma_f32_16x16x32_bf16 v[40:43], v[138:141], v[178:181], v[40:43]
	v_mfma_f32_16x16x32_bf16 v[44:47], v[154:157], v[178:181], v[44:47]
	v_mfma_f32_16x16x32_bf16 v[32:35], v[138:141], v[186:189], v[32:35]
	v_mfma_f32_16x16x32_bf16 v[36:39], v[154:157], v[186:189], v[36:39]
	v_mfma_f32_16x16x32_bf16 v[60:63], v[150:153], v[166:169], v[60:63]
	v_mfma_f32_16x16x32_bf16 v[68:71], v[158:161], v[166:169], v[68:71]
	v_mfma_f32_16x16x32_bf16 v[48:51], v[150:153], v[174:177], v[48:51]
	v_mfma_f32_16x16x32_bf16 v[52:55], v[158:161], v[174:177], v[52:55]
	v_mfma_f32_16x16x32_bf16 v[40:43], v[150:153], v[182:185], v[40:43]
	v_mfma_f32_16x16x32_bf16 v[44:47], v[158:161], v[182:185], v[44:47]
	v_mfma_f32_16x16x32_bf16 v[32:35], v[150:153], v[190:193], v[32:35]
	v_mfma_f32_16x16x32_bf16 v[36:39], v[158:161], v[190:193], v[36:39]
	s_setprio 0
	s_barrier
	s_add_i32 s18, s18, s4
	s_add_i32 vcc_hi, s60, 2
	s_cmp_eq_u32 vcc_hi, s83
	s_cselect_b32 s100, s16, s81
	s_cselect_b32 s101, s17, s82
	s_add_u32 s100, s100, s84
	s_addc_u32 s101, s101, 0
	s_add_u32 s100, s100, 0x80
	s_addc_u32 s101, s101, 0
	s_mov_b32 m0, s18
	s_nop 0
	global_load_lds_dwordx4 v198, s[100:101]
	s_add_i32 m0, s18, 0x2000
	s_nop 0
	global_load_lds_dwordx4 v128, s[100:101]
	s_add_u32 s20, s20, 0x100
	s_addc_u32 s21, s21, 0
	s_add_u32 s81, s81, 0x100
	s_addc_u32 s82, s82, 0
	s_mov_b32 s18, s83
	s_cmp_ge_u32 s83, s57
	s_waitcnt vmcnt(6)
	s_barrier
	s_setprio 1
	v_mfma_f32_16x16x32_bf16 v[120:123], v[194:197], v[162:165], v[120:123]
	v_mfma_f32_16x16x32_bf16 v[124:127], v[204:207], v[162:165], v[124:127]
	v_mfma_f32_16x16x32_bf16 v[112:115], v[194:197], v[170:173], v[112:115]
	v_mfma_f32_16x16x32_bf16 v[116:119], v[204:207], v[170:173], v[116:119]
	v_mfma_f32_16x16x32_bf16 v[104:107], v[194:197], v[178:181], v[104:107]
	v_mfma_f32_16x16x32_bf16 v[108:111], v[204:207], v[178:181], v[108:111]
	v_mfma_f32_16x16x32_bf16 v[92:95], v[194:197], v[186:189], v[92:95]
	v_mfma_f32_16x16x32_bf16 v[100:103], v[204:207], v[186:189], v[100:103]
	v_mfma_f32_16x16x32_bf16 v[120:123], v[200:203], v[166:169], v[120:123]
	v_mfma_f32_16x16x32_bf16 v[124:127], v[208:211], v[166:169], v[124:127]
	v_mfma_f32_16x16x32_bf16 v[112:115], v[200:203], v[174:177], v[112:115]
	v_mfma_f32_16x16x32_bf16 v[116:119], v[208:211], v[174:177], v[116:119]
	v_mfma_f32_16x16x32_bf16 v[104:107], v[200:203], v[182:185], v[104:107]
	v_mfma_f32_16x16x32_bf16 v[108:111], v[208:211], v[182:185], v[108:111]
	v_mfma_f32_16x16x32_bf16 v[92:95], v[200:203], v[190:193], v[92:95]
	v_mfma_f32_16x16x32_bf16 v[100:103], v[208:211], v[190:193], v[100:103]
	s_setprio 0
	s_barrier
	s_cbranch_scc0 .LBB0_743
